# p[l]->bf16 copy loop in phase_convert: 5 passes with all loads issued before the converts/stores (original loop kept as tail)
# speedup vs baseline: 1.0049x; 1.0049x over previous
; __device__ __forceinline__ const float* lin(const Params& P, int k) { return P.in[k] + lzero(); }
; __device__ __forceinline__ size_t lo(size_t x) { asm volatile("" : "+s"(x)); return x; }
; DI unsigned pk2(float lo, float hi) { const f32x2 v = {lo, hi}; return __builtin_bit_cast(unsigned, __builtin_convertvector(v, bf16n2)); }
; DI void phase_convert(LAS unsigned char* lds, const Params& P, int l) {
;     ...
;     { bf16_t* p16 = (bf16_t*)(ws + lo(WS_P16)); const float* pp = lin(P, 7) + (size_t)l * MPR * 256; const float* ps = lin(P, 8) + (size_t)l * 512 * 256;
;       #pragma clang loop unroll(disable) vectorize(disable)
;       for (int i = blockIdx.x * 512 + tid; i < MT * 256 / 4; i += G * 512) { const size_t e = (size_t)i * 4; const f32x4 v = (e < (size_t)MPR * 256) ? *(const f32x4*)(pp + e) : *(const f32x4*)(ps + (e - (size_t)MPR * 256));
;           u32x2 w; w.x = pk2(v[0], v[1]); w.y = pk2(v[2], v[3]); *(u32x2*)(p16 + e) = w; } }
.LBB0_114:
	s_waitcnt vmcnt(8)
	s_mov_b64 s[4:5], 0x200000
	v_lshl_add_u64 v[12:13], v[6:7], 0, s[42:43]
	v_lshl_add_u64 v[14:15], v[4:5], 0, s[42:43]
	v_cmp_gt_u64_e32 vcc, s[4:5], v[10:11]
	v_add_u32_e32 v2, s74, v2
	s_add_u32 s42, s42, s8
	s_addc_u32 s43, s43, s9
	v_cndmask_b32_e32 v13, v15, v13, vcc
	v_cndmask_b32_e32 v12, v14, v12, vcc
	global_load_dwordx4 v[56:59], v[12:13], off
	s_mov_b64 s[60:61], exec
	s_mov_b32 s4, 0x87fff
	v_cmp_lt_i32_e32 vcc, s4, v2
	v_lshl_add_u64 v[10:11], v[10:11], 0, s[10:11]
	s_nop 1
	s_or_b64 s[40:41], vcc, s[40:41]
	s_andn2_b64 exec, exec, s[40:41]
	s_mov_b64 s[4:5], 0x200000
	v_lshl_add_u64 v[12:13], v[6:7], 0, s[42:43]
	v_lshl_add_u64 v[14:15], v[4:5], 0, s[42:43]
	v_cmp_gt_u64_e32 vcc, s[4:5], v[10:11]
	v_add_u32_e32 v2, s74, v2
	s_add_u32 s42, s42, s8
	s_addc_u32 s43, s43, s9
	v_cndmask_b32_e32 v13, v15, v13, vcc
	v_cndmask_b32_e32 v12, v14, v12, vcc
	global_load_dwordx4 v[60:63], v[12:13], off
	s_mov_b64 s[62:63], exec
	s_mov_b32 s4, 0x87fff
	v_cmp_lt_i32_e32 vcc, s4, v2
	v_lshl_add_u64 v[10:11], v[10:11], 0, s[10:11]
	s_nop 1
	s_or_b64 s[40:41], vcc, s[40:41]
	s_andn2_b64 exec, exec, s[40:41]
	s_mov_b64 s[4:5], 0x200000
	v_lshl_add_u64 v[12:13], v[6:7], 0, s[42:43]
	v_lshl_add_u64 v[14:15], v[4:5], 0, s[42:43]
	v_cmp_gt_u64_e32 vcc, s[4:5], v[10:11]
	v_add_u32_e32 v2, s74, v2
	s_add_u32 s42, s42, s8
	s_addc_u32 s43, s43, s9
	v_cndmask_b32_e32 v13, v15, v13, vcc
	v_cndmask_b32_e32 v12, v14, v12, vcc
	global_load_dwordx4 v[64:67], v[12:13], off
	s_mov_b64 s[64:65], exec
	s_mov_b32 s4, 0x87fff
	v_cmp_lt_i32_e32 vcc, s4, v2
	v_lshl_add_u64 v[10:11], v[10:11], 0, s[10:11]
	s_nop 1
	s_or_b64 s[40:41], vcc, s[40:41]
	s_andn2_b64 exec, exec, s[40:41]
	s_mov_b64 s[4:5], 0x200000
	v_lshl_add_u64 v[12:13], v[6:7], 0, s[42:43]
	v_lshl_add_u64 v[14:15], v[4:5], 0, s[42:43]
	v_cmp_gt_u64_e32 vcc, s[4:5], v[10:11]
	v_add_u32_e32 v2, s74, v2
	s_add_u32 s42, s42, s8
	s_addc_u32 s43, s43, s9
	v_cndmask_b32_e32 v13, v15, v13, vcc
	v_cndmask_b32_e32 v12, v14, v12, vcc
	global_load_dwordx4 v[68:71], v[12:13], off
	s_mov_b64 s[66:67], exec
	s_mov_b32 s4, 0x87fff
	v_cmp_lt_i32_e32 vcc, s4, v2
	v_lshl_add_u64 v[10:11], v[10:11], 0, s[10:11]
	s_nop 1
	s_or_b64 s[40:41], vcc, s[40:41]
	s_andn2_b64 exec, exec, s[40:41]
	s_mov_b64 s[4:5], 0x200000
	v_lshl_add_u64 v[12:13], v[6:7], 0, s[42:43]
	v_lshl_add_u64 v[14:15], v[4:5], 0, s[42:43]
	v_cmp_gt_u64_e32 vcc, s[4:5], v[10:11]
	v_add_u32_e32 v2, s74, v2
	s_add_u32 s42, s42, s8
	s_addc_u32 s43, s43, s9
	v_cndmask_b32_e32 v13, v15, v13, vcc
	v_cndmask_b32_e32 v12, v14, v12, vcc
	global_load_dwordx4 v[72:75], v[12:13], off
	s_mov_b64 s[68:69], exec
	s_mov_b32 s4, 0x87fff
	v_cmp_lt_i32_e32 vcc, s4, v2
	v_lshl_add_u64 v[10:11], v[10:11], 0, s[10:11]
	s_nop 1
	s_or_b64 s[40:41], vcc, s[40:41]
	s_andn2_b64 exec, exec, s[40:41]
	s_mov_b64 s[70:71], exec
	s_mov_b64 exec, s[60:61]
	s_waitcnt vmcnt(4)
	v_cvt_pk_bf16_f32 v12, v56, v57
	v_cvt_pk_bf16_f32 v13, v58, v59
	global_store_dwordx2 v[8:9], v[12:13], off
	v_lshl_add_u64 v[8:9], v[8:9], 0, s[12:13]
	s_mov_b64 exec, s[62:63]
	s_waitcnt vmcnt(4)
	v_cvt_pk_bf16_f32 v12, v60, v61
	v_cvt_pk_bf16_f32 v13, v62, v63
	global_store_dwordx2 v[8:9], v[12:13], off
	v_lshl_add_u64 v[8:9], v[8:9], 0, s[12:13]
	s_mov_b64 exec, s[64:65]
	s_waitcnt vmcnt(4)
	v_cvt_pk_bf16_f32 v12, v64, v65
	v_cvt_pk_bf16_f32 v13, v66, v67
	global_store_dwordx2 v[8:9], v[12:13], off
	v_lshl_add_u64 v[8:9], v[8:9], 0, s[12:13]
	s_mov_b64 exec, s[66:67]
	s_waitcnt vmcnt(4)
	v_cvt_pk_bf16_f32 v12, v68, v69
	v_cvt_pk_bf16_f32 v13, v70, v71
	global_store_dwordx2 v[8:9], v[12:13], off
	v_lshl_add_u64 v[8:9], v[8:9], 0, s[12:13]
	s_mov_b64 exec, s[68:69]
	s_waitcnt vmcnt(4)
	v_cvt_pk_bf16_f32 v12, v72, v73
	v_cvt_pk_bf16_f32 v13, v74, v75
	global_store_dwordx2 v[8:9], v[12:13], off
	v_lshl_add_u64 v[8:9], v[8:9], 0, s[12:13]
	s_mov_b64 exec, s[70:71]
	s_cbranch_execz .LBB0_115
